# diff and MLA window check: any-lane test on the lane maximum first, cross-half ds_bpermute exchange only when the window is left
# baseline (speedup 1.0000x reference)
.LBB0_164:
	s_and_b32 s68, s50, 2
	s_cbranch_scc1 .LBB0_167
	v_max_f32_e32 v119, v47, v47
	v_max_f32_e32 v120, v63, v63
	v_max_f32_e32 v119, v120, v119
	v_max3_f32 v120, v119, v48, v49
	v_max3_f32 v119, v119, v32, v33
	s_nop 0
	v_max3_f32 v119, v119, v34, v35
	v_max3_f32 v120, v120, v50, v51
	s_nop 0
	v_max3_f32 v119, v119, v36, v37
	v_max3_f32 v120, v120, v52, v53
	s_nop 0
	v_max3_f32 v119, v119, v38, v39
	v_max3_f32 v120, v120, v54, v55
	s_nop 0
	v_max3_f32 v119, v119, v40, v41
	v_max3_f32 v120, v120, v56, v57
	s_nop 0
	v_max3_f32 v119, v119, v42, v43
	v_max3_f32 v120, v120, v58, v59
	s_nop 0
	v_max3_f32 v119, v119, v44, v45
	v_max3_f32 v120, v120, v60, v61
	s_nop 0
	v_max3_f32 v119, v120, v119, v62
	s_nop 0
	v_max3_f32 v119, v119, v46, v119
	v_cmp_lt_f32_e32 vcc, s7, v119
	s_cbranch_vccz .LBB0_167
	ds_bpermute_b32 v120, v178, v119
	v_max_f32_e32 v119, v119, v119
	s_waitcnt lgkmcnt(0)
	v_max_f32_e32 v120, v120, v120
	v_max_f32_e32 v119, v119, v120
	v_cmp_lt_f32_e32 vcc, s7, v119
	s_nop 1
	s_nop 0
	v_cndmask_b32_e32 v119, 0, v119, vcc
	v_exp_f32_e64 v120, -v119
	v_sub_f32_e32 v47, v47, v119
	v_sub_f32_e32 v46, v46, v119
	v_sub_f32_e32 v45, v45, v119
	v_pk_mul_f32 v[14:15], v[14:15], v[120:121] op_sel_hi:[1,0]
	v_pk_mul_f32 v[12:13], v[12:13], v[120:121] op_sel_hi:[1,0]
	v_pk_mul_f32 v[10:11], v[10:11], v[120:121] op_sel_hi:[1,0]
	v_pk_mul_f32 v[8:9], v[8:9], v[120:121] op_sel_hi:[1,0]
	v_pk_mul_f32 v[6:7], v[6:7], v[120:121] op_sel_hi:[1,0]
	v_pk_mul_f32 v[4:5], v[4:5], v[120:121] op_sel_hi:[1,0]
	v_pk_mul_f32 v[2:3], v[2:3], v[120:121] op_sel_hi:[1,0]
	v_pk_mul_f32 v[0:1], v[0:1], v[120:121] op_sel_hi:[1,0]
	v_pk_mul_f32 v[30:31], v[30:31], v[120:121] op_sel_hi:[1,0]
	v_pk_mul_f32 v[28:29], v[28:29], v[120:121] op_sel_hi:[1,0]
	v_pk_mul_f32 v[26:27], v[26:27], v[120:121] op_sel_hi:[1,0]
	v_pk_mul_f32 v[24:25], v[24:25], v[120:121] op_sel_hi:[1,0]
	v_pk_mul_f32 v[22:23], v[22:23], v[120:121] op_sel_hi:[1,0]
	v_pk_mul_f32 v[20:21], v[20:21], v[120:121] op_sel_hi:[1,0]
	v_pk_mul_f32 v[18:19], v[18:19], v[120:121] op_sel_hi:[1,0]
	v_pk_mul_f32 v[16:17], v[16:17], v[120:121] op_sel_hi:[1,0]
	v_mul_f32_e32 v175, v175, v120
	v_sub_f32_e32 v44, v44, v119
	v_sub_f32_e32 v43, v43, v119
	v_sub_f32_e32 v42, v42, v119
	v_sub_f32_e32 v41, v41, v119
	v_sub_f32_e32 v40, v40, v119
	v_sub_f32_e32 v39, v39, v119
	v_sub_f32_e32 v38, v38, v119
	v_sub_f32_e32 v37, v37, v119
	v_sub_f32_e32 v36, v36, v119
	v_sub_f32_e32 v35, v35, v119
	v_sub_f32_e32 v34, v34, v119
	v_sub_f32_e32 v33, v33, v119
	v_sub_f32_e32 v32, v32, v119
	v_sub_f32_e32 v95, v95, v119
	v_sub_f32_e32 v94, v94, v119
	v_sub_f32_e32 v93, v93, v119
	v_sub_f32_e32 v92, v92, v119
	v_sub_f32_e32 v91, v91, v119
	v_sub_f32_e32 v90, v90, v119
	v_sub_f32_e32 v89, v89, v119
	v_sub_f32_e32 v88, v88, v119
	v_sub_f32_e32 v87, v87, v119
	v_sub_f32_e32 v86, v86, v119
	v_sub_f32_e32 v85, v85, v119
	v_sub_f32_e32 v84, v84, v119
	v_sub_f32_e32 v83, v83, v119
	v_sub_f32_e32 v82, v82, v119
	v_sub_f32_e32 v81, v81, v119
	v_sub_f32_e32 v80, v80, v119
	v_sub_f32_e32 v79, v79, v119
	v_sub_f32_e32 v78, v78, v119
	v_sub_f32_e32 v77, v77, v119
	v_sub_f32_e32 v76, v76, v119
	v_sub_f32_e32 v75, v75, v119
	v_sub_f32_e32 v74, v74, v119
	v_sub_f32_e32 v73, v73, v119
	v_sub_f32_e32 v72, v72, v119
	v_sub_f32_e32 v71, v71, v119
	v_sub_f32_e32 v70, v70, v119
	v_sub_f32_e32 v69, v69, v119
	v_sub_f32_e32 v68, v68, v119
	v_sub_f32_e32 v67, v67, v119
	v_sub_f32_e32 v66, v66, v119
	v_sub_f32_e32 v65, v65, v119
	v_sub_f32_e32 v64, v64, v119
	v_sub_f32_e32 v63, v63, v119
	v_sub_f32_e32 v62, v62, v119
	v_sub_f32_e32 v61, v61, v119
	v_sub_f32_e32 v60, v60, v119
	v_sub_f32_e32 v59, v59, v119
	v_sub_f32_e32 v58, v58, v119
	v_sub_f32_e32 v57, v57, v119
	v_sub_f32_e32 v56, v56, v119
	v_sub_f32_e32 v55, v55, v119
	v_sub_f32_e32 v54, v54, v119
	v_sub_f32_e32 v53, v53, v119
	v_sub_f32_e32 v52, v52, v119
	v_sub_f32_e32 v51, v51, v119
	v_sub_f32_e32 v50, v50, v119
	v_sub_f32_e32 v49, v49, v119
	v_sub_f32_e32 v48, v48, v119
	v_add_f32_e32 v108, v108, v119
	s_mov_b64 s[28:29], -1

.LBB0_195:
	s_and_b32 s18, s17, 2
	s_cbranch_scc1 .LBB0_198
	v_max_f32_e32 v150, v79, v79
	v_max_f32_e32 v151, v95, v95
	v_max_f32_e32 v150, v151, v150
	v_max3_f32 v151, v150, v80, v81
	v_max3_f32 v150, v150, v64, v65
	s_nop 0
	v_max3_f32 v150, v150, v66, v67
	v_max3_f32 v151, v151, v82, v83
	s_nop 0
	v_max3_f32 v150, v150, v68, v69
	v_max3_f32 v151, v151, v84, v85
	s_nop 0
	v_max3_f32 v150, v150, v70, v71
	v_max3_f32 v151, v151, v86, v87
	s_nop 0
	v_max3_f32 v150, v150, v72, v73
	v_max3_f32 v151, v151, v88, v89
	s_nop 0
	v_max3_f32 v150, v150, v74, v75
	v_max3_f32 v151, v151, v90, v91
	s_nop 0
	v_max3_f32 v150, v150, v76, v77
	v_max3_f32 v151, v151, v92, v93
	s_nop 0
	v_max3_f32 v150, v151, v150, v94
	s_nop 0
	v_max3_f32 v150, v150, v78, v150
	v_cmp_lt_f32_e32 vcc, s7, v150
	s_cbranch_vccz .LBB0_198
	ds_bpermute_b32 v151, v178, v150
	v_max_f32_e32 v150, v150, v150
	s_waitcnt lgkmcnt(0)
	v_max_f32_e32 v151, v151, v151
	v_max_f32_e32 v150, v150, v151
	v_cmp_lt_f32_e32 vcc, s7, v150
	s_nop 1
	s_nop 0
	v_cndmask_b32_e32 v151, 0, v150, vcc
	v_exp_f32_e64 v150, -v151
	v_sub_f32_e32 v79, v79, v151
	v_sub_f32_e32 v78, v78, v151
	v_sub_f32_e32 v77, v77, v151
	v_pk_mul_f32 v[62:63], v[62:63], v[150:151] op_sel_hi:[1,0]
	v_pk_mul_f32 v[60:61], v[60:61], v[150:151] op_sel_hi:[1,0]
	v_pk_mul_f32 v[58:59], v[58:59], v[150:151] op_sel_hi:[1,0]
	v_pk_mul_f32 v[56:57], v[56:57], v[150:151] op_sel_hi:[1,0]
	v_pk_mul_f32 v[54:55], v[54:55], v[150:151] op_sel_hi:[1,0]
	v_pk_mul_f32 v[52:53], v[52:53], v[150:151] op_sel_hi:[1,0]
	v_pk_mul_f32 v[50:51], v[50:51], v[150:151] op_sel_hi:[1,0]
	v_pk_mul_f32 v[48:49], v[48:49], v[150:151] op_sel_hi:[1,0]
	v_pk_mul_f32 v[46:47], v[46:47], v[150:151] op_sel_hi:[1,0]
	v_pk_mul_f32 v[44:45], v[44:45], v[150:151] op_sel_hi:[1,0]
	v_pk_mul_f32 v[42:43], v[42:43], v[150:151] op_sel_hi:[1,0]
	v_pk_mul_f32 v[40:41], v[40:41], v[150:151] op_sel_hi:[1,0]
	v_pk_mul_f32 v[38:39], v[38:39], v[150:151] op_sel_hi:[1,0]
	v_pk_mul_f32 v[36:37], v[36:37], v[150:151] op_sel_hi:[1,0]
	v_pk_mul_f32 v[34:35], v[34:35], v[150:151] op_sel_hi:[1,0]
	v_pk_mul_f32 v[32:33], v[32:33], v[150:151] op_sel_hi:[1,0]
	v_mul_f32_e32 v184, v184, v150
	v_sub_f32_e32 v76, v76, v151
	v_sub_f32_e32 v75, v75, v151
	v_sub_f32_e32 v74, v74, v151
	v_sub_f32_e32 v73, v73, v151
	v_sub_f32_e32 v72, v72, v151
	v_sub_f32_e32 v71, v71, v151
	v_sub_f32_e32 v70, v70, v151
	v_sub_f32_e32 v69, v69, v151
	v_sub_f32_e32 v68, v68, v151
	v_sub_f32_e32 v67, v67, v151
	v_sub_f32_e32 v66, v66, v151
	v_sub_f32_e32 v65, v65, v151
	v_sub_f32_e32 v64, v64, v151
	v_sub_f32_e32 v127, v127, v151
	v_sub_f32_e32 v126, v126, v151
	v_sub_f32_e32 v125, v125, v151
	v_sub_f32_e32 v124, v124, v151
	v_sub_f32_e32 v123, v123, v151
	v_sub_f32_e32 v122, v122, v151
	v_sub_f32_e32 v121, v121, v151
	v_sub_f32_e32 v120, v120, v151
	v_sub_f32_e32 v119, v119, v151
	v_sub_f32_e32 v118, v118, v151
	v_sub_f32_e32 v117, v117, v151
	v_sub_f32_e32 v116, v116, v151
	v_sub_f32_e32 v115, v115, v151
	v_sub_f32_e32 v114, v114, v151
	v_sub_f32_e32 v113, v113, v151
	v_sub_f32_e32 v112, v112, v151
	v_sub_f32_e32 v111, v111, v151
	v_sub_f32_e32 v110, v110, v151
	v_sub_f32_e32 v109, v109, v151
	v_sub_f32_e32 v108, v108, v151
	v_sub_f32_e32 v107, v107, v151
	v_sub_f32_e32 v106, v106, v151
	v_sub_f32_e32 v105, v105, v151
	v_sub_f32_e32 v104, v104, v151
	v_sub_f32_e32 v103, v103, v151
	v_sub_f32_e32 v102, v102, v151
	v_sub_f32_e32 v101, v101, v151
	v_sub_f32_e32 v100, v100, v151
	v_sub_f32_e32 v99, v99, v151
	v_sub_f32_e32 v98, v98, v151
	v_sub_f32_e32 v97, v97, v151
	v_sub_f32_e32 v96, v96, v151
	v_sub_f32_e32 v95, v95, v151
	v_sub_f32_e32 v94, v94, v151
	v_sub_f32_e32 v93, v93, v151
	v_sub_f32_e32 v92, v92, v151
	v_sub_f32_e32 v91, v91, v151
	v_sub_f32_e32 v90, v90, v151
	v_sub_f32_e32 v89, v89, v151
	v_sub_f32_e32 v88, v88, v151
	v_sub_f32_e32 v87, v87, v151
	v_sub_f32_e32 v86, v86, v151
	v_sub_f32_e32 v85, v85, v151
	v_sub_f32_e32 v84, v84, v151
	v_sub_f32_e32 v83, v83, v151
	v_sub_f32_e32 v82, v82, v151
	v_sub_f32_e32 v81, v81, v151
	v_sub_f32_e32 v80, v80, v151
	v_add_f32_e32 v144, v144, v151
	s_mov_b64 s[28:29], -1

.LBB0_227:
	s_and_b32 s2, s19, 2
	s_cmp_eq_u32 s2, 0
	s_cselect_b64 s[42:43], -1, 0
	s_cmp_lg_u32 s2, 0
	s_cbranch_scc1 .LBB0_230
	v_max_f32_e32 v142, v47, v47
	v_max_f32_e32 v143, v63, v63
	v_max_f32_e32 v142, v143, v142
	v_max3_f32 v143, v142, v48, v49
	v_max3_f32 v142, v142, v32, v33
	s_nop 0
	v_max3_f32 v142, v142, v34, v35
	v_max3_f32 v143, v143, v50, v51
	s_nop 0
	v_max3_f32 v142, v142, v36, v37
	v_max3_f32 v143, v143, v52, v53
	s_nop 0
	v_max3_f32 v142, v142, v38, v39
	v_max3_f32 v143, v143, v54, v55
	s_nop 0
	v_max3_f32 v142, v142, v40, v41
	v_max3_f32 v143, v143, v56, v57
	s_nop 0
	v_max3_f32 v142, v142, v42, v43
	v_max3_f32 v143, v143, v58, v59
	s_nop 0
	v_max3_f32 v142, v142, v44, v45
	v_max3_f32 v143, v143, v60, v61
	s_nop 0
	v_max3_f32 v142, v143, v142, v62
	s_nop 0
	v_max3_f32 v142, v142, v46, v142
	v_cmp_lt_f32_e32 vcc, s7, v142
	s_cbranch_vccz .LBB0_230
	ds_bpermute_b32 v143, v144, v142
	v_max_f32_e32 v142, v142, v142
	s_waitcnt lgkmcnt(0)
	v_max_f32_e32 v143, v143, v143
	v_max_f32_e32 v142, v142, v143
	v_cmp_lt_f32_e32 vcc, s7, v142
	s_nop 1
	s_nop 0
	v_cndmask_b32_e32 v143, 0, v142, vcc
	v_exp_f32_e64 v142, -v143
	v_sub_f32_e32 v47, v47, v143
	v_sub_f32_e32 v46, v46, v143
	v_sub_f32_e32 v45, v45, v143
	v_pk_mul_f32 v[14:15], v[14:15], v[142:143] op_sel_hi:[1,0]
	v_pk_mul_f32 v[12:13], v[12:13], v[142:143] op_sel_hi:[1,0]
	v_pk_mul_f32 v[10:11], v[10:11], v[142:143] op_sel_hi:[1,0]
	v_pk_mul_f32 v[8:9], v[8:9], v[142:143] op_sel_hi:[1,0]
	v_pk_mul_f32 v[6:7], v[6:7], v[142:143] op_sel_hi:[1,0]
	v_pk_mul_f32 v[4:5], v[4:5], v[142:143] op_sel_hi:[1,0]
	v_pk_mul_f32 v[2:3], v[2:3], v[142:143] op_sel_hi:[1,0]
	v_pk_mul_f32 v[0:1], v[0:1], v[142:143] op_sel_hi:[1,0]
	v_pk_mul_f32 v[30:31], v[30:31], v[142:143] op_sel_hi:[1,0]
	v_pk_mul_f32 v[28:29], v[28:29], v[142:143] op_sel_hi:[1,0]
	v_pk_mul_f32 v[26:27], v[26:27], v[142:143] op_sel_hi:[1,0]
	v_pk_mul_f32 v[24:25], v[24:25], v[142:143] op_sel_hi:[1,0]
	v_pk_mul_f32 v[22:23], v[22:23], v[142:143] op_sel_hi:[1,0]
	v_pk_mul_f32 v[20:21], v[20:21], v[142:143] op_sel_hi:[1,0]
	v_pk_mul_f32 v[18:19], v[18:19], v[142:143] op_sel_hi:[1,0]
	v_pk_mul_f32 v[16:17], v[16:17], v[142:143] op_sel_hi:[1,0]
	v_mul_f32_e32 v149, v149, v142
	v_sub_f32_e32 v44, v44, v143
	v_sub_f32_e32 v43, v43, v143
	v_sub_f32_e32 v42, v42, v143
	v_sub_f32_e32 v41, v41, v143
	v_sub_f32_e32 v40, v40, v143
	v_sub_f32_e32 v39, v39, v143
	v_sub_f32_e32 v38, v38, v143
	v_sub_f32_e32 v37, v37, v143
	v_sub_f32_e32 v36, v36, v143
	v_sub_f32_e32 v35, v35, v143
	v_sub_f32_e32 v34, v34, v143
	v_sub_f32_e32 v33, v33, v143
	v_sub_f32_e32 v32, v32, v143
	v_sub_f32_e32 v95, v95, v143
	v_sub_f32_e32 v94, v94, v143
	v_sub_f32_e32 v93, v93, v143
	v_sub_f32_e32 v92, v92, v143
	v_sub_f32_e32 v91, v91, v143
	v_sub_f32_e32 v90, v90, v143
	v_sub_f32_e32 v89, v89, v143
	v_sub_f32_e32 v88, v88, v143
	v_sub_f32_e32 v87, v87, v143
	v_sub_f32_e32 v86, v86, v143
	v_sub_f32_e32 v85, v85, v143
	v_sub_f32_e32 v84, v84, v143
	v_sub_f32_e32 v83, v83, v143
	v_sub_f32_e32 v82, v82, v143
	v_sub_f32_e32 v81, v81, v143
	v_sub_f32_e32 v80, v80, v143
	v_sub_f32_e32 v79, v79, v143
	v_sub_f32_e32 v78, v78, v143
	v_sub_f32_e32 v77, v77, v143
	v_sub_f32_e32 v76, v76, v143
	v_sub_f32_e32 v75, v75, v143
	v_sub_f32_e32 v74, v74, v143
	v_sub_f32_e32 v73, v73, v143
	v_sub_f32_e32 v72, v72, v143
	v_sub_f32_e32 v71, v71, v143
	v_sub_f32_e32 v70, v70, v143
	v_sub_f32_e32 v69, v69, v143
	v_sub_f32_e32 v68, v68, v143
	v_sub_f32_e32 v67, v67, v143
	v_sub_f32_e32 v66, v66, v143
	v_sub_f32_e32 v65, v65, v143
	v_sub_f32_e32 v64, v64, v143
	v_sub_f32_e32 v63, v63, v143
	v_sub_f32_e32 v62, v62, v143
	v_sub_f32_e32 v61, v61, v143
	v_sub_f32_e32 v60, v60, v143
	v_sub_f32_e32 v59, v59, v143
	v_sub_f32_e32 v58, v58, v143
	v_sub_f32_e32 v57, v57, v143
	v_sub_f32_e32 v56, v56, v143
	v_sub_f32_e32 v55, v55, v143
	v_sub_f32_e32 v54, v54, v143
	v_sub_f32_e32 v53, v53, v143
	v_sub_f32_e32 v52, v52, v143
	v_sub_f32_e32 v51, v51, v143
	v_sub_f32_e32 v50, v50, v143
	v_sub_f32_e32 v49, v49, v143
	v_sub_f32_e32 v48, v48, v143
	v_add_f32_e32 v128, v128, v143
	s_mov_b64 s[28:29], -1
